# MLA: second tile's K fragments fetched from LDS during the first tile's softmax (separate V fragment registers, constants restored at phase exit)
# baseline (speedup 1.0000x reference)
; #define LAS __attribute__((address_space(3)))
; __device__ __forceinline__ void mla_unit(const Ctx& C, const Params& p, int unit) {
;     ...
;             const LAS unsigned char* Kb = lds + ((kp & 1) * 2 + sub) * ABUF; const LAS unsigned char* Vb = Kb + AK_BYTES;
;             const int k0 = kt * 64;
;             f32x4 s[2][4];
; #pragma unroll
;             for (int g = 0; g < 2; ++g)
; #pragma unroll
;                 for (int blk = 0; blk < 4; ++blk) s[g][blk] = (f32x4){0.f, 0.f, 0.f, 0.f};
; #pragma unroll
;             for (int kk = 0; kk < 3; ++kk)
; #pragma unroll
;                 for (int blk = 0; blk < 4; ++blk) {
;                     const bf16x8 kf = *(const LAS bf16x8*)(Kb + (blk * 16 + fr) * AK_ROW + (kk * 32 + fq * 8) * 2);
; #pragma unroll
;                     for (int g = 0; g < 2; ++g) s[g][blk] = __builtin_amdgcn_mfma_f32_16x16x32_bf16(kf, qf[g][kk], s[g][blk], 0, 0, 0);
;                 }
;             const bool need_mask = (k0 + 63 > q0w);
;             bf16x8 pf[2][2];
; #pragma unroll
;             for (int g = 0; g < 2; ++g) {
;                 const int qi = q0w + 16 * g + fr;
;                 if (need_mask) {
;                     asm volatile("" ::: "memory");
; #pragma unroll
;                     for (int blk = 0; blk < 4; ++blk)
; #pragma unroll
;                         for (int j = 0; j < 4; ++j) { const int key = k0 + blk * 16 + fq * 4 + j; if (key > qi) s[g][blk][j] = -1e30f; }
;                     asm volatile("" ::: "memory");
;                 }
.LBB0_514:
	s_or_b32 s1, s4, s88
	s_mulk_i32 s1, 0x5800
	v_add_u32_e32 v2, s1, v246
	s_cmp_eq_u32 s4, 1
	s_cbranch_scc1 .Lmla_kdone
	ds_read_b128 v[198:201], v2
	ds_read_b128 v[210:213], v2 offset:1024
	ds_read_b128 v[222:225], v2 offset:2048
	ds_read_b128 v[234:237], v2 offset:3072
	ds_read_b128 v[202:205], v2 offset:4096
	ds_read_b128 v[214:217], v2 offset:5120
	ds_read_b128 v[226:229], v2 offset:6144
	ds_read_b128 v[238:241], v2 offset:7168
	ds_read_b128 v[206:209], v2 offset:8192
	ds_read_b128 v[218:221], v2 offset:9216
	ds_read_b128 v[230:233], v2 offset:10240
	ds_read_b128 v[242:245], v2 offset:11264
.Lmla_kdone:
	s_lshl_b32 s0, s0, 6
	s_or_b32 s1, s0, 63
	s_waitcnt lgkmcnt(8)
	v_mfma_f32_16x16x32_bf16 v[84:87], v[198:201], v[12:15], 0
	v_mfma_f32_16x16x32_bf16 v[100:103], v[198:201], v[16:19], 0
	v_mfma_f32_16x16x32_bf16 v[88:91], v[210:213], v[12:15], 0
	v_mfma_f32_16x16x32_bf16 v[104:107], v[210:213], v[16:19], 0
	v_mfma_f32_16x16x32_bf16 v[92:95], v[222:225], v[12:15], 0
	v_mfma_f32_16x16x32_bf16 v[108:111], v[222:225], v[16:19], 0
	v_mfma_f32_16x16x32_bf16 v[96:99], v[234:237], v[12:15], 0
	v_mfma_f32_16x16x32_bf16 v[112:115], v[234:237], v[16:19], 0
	ds_read_b128 v[134:137], v2 offset:13312
	ds_read_b128 v[138:141], v2 offset:14336
	ds_read_b128 v[142:145], v2 offset:15360
	ds_read_b128 v[146:149], v2 offset:16384
	s_waitcnt lgkmcnt(8)
	v_mfma_f32_16x16x32_bf16 v[84:87], v[202:205], v[4:7], v[84:87]
	v_mfma_f32_16x16x32_bf16 v[100:103], v[202:205], v[8:11], v[100:103]
	v_mfma_f32_16x16x32_bf16 v[88:91], v[214:217], v[4:7], v[88:91]
	v_mfma_f32_16x16x32_bf16 v[104:107], v[214:217], v[8:11], v[104:107]
	v_mfma_f32_16x16x32_bf16 v[92:95], v[226:229], v[4:7], v[92:95]
	v_mfma_f32_16x16x32_bf16 v[108:111], v[226:229], v[8:11], v[108:111]
	v_mfma_f32_16x16x32_bf16 v[96:99], v[238:241], v[4:7], v[96:99]
	v_mfma_f32_16x16x32_bf16 v[112:115], v[238:241], v[8:11], v[112:115]
	ds_read_b128 v[160:163], v2 offset:17408
	ds_read_b128 v[164:167], v2 offset:18432
	ds_read_b128 v[168:171], v2 offset:19456
	ds_read_b128 v[156:159], v2 offset:20480
	s_waitcnt lgkmcnt(8)
	v_mfma_f32_16x16x32_bf16 v[84:87], v[206:209], v[44:47], v[84:87]
	v_mfma_f32_16x16x32_bf16 v[100:103], v[206:209], v[60:63], v[100:103]
	v_mfma_f32_16x16x32_bf16 v[88:91], v[218:221], v[44:47], v[88:91]
	v_mfma_f32_16x16x32_bf16 v[104:107], v[218:221], v[60:63], v[104:107]
	v_mfma_f32_16x16x32_bf16 v[92:95], v[230:233], v[44:47], v[92:95]
	v_mfma_f32_16x16x32_bf16 v[108:111], v[230:233], v[60:63], v[108:111]
	v_mfma_f32_16x16x32_bf16 v[96:99], v[242:245], v[44:47], v[96:99]
	v_mfma_f32_16x16x32_bf16 v[112:115], v[242:245], v[60:63], v[112:115]
	s_cmp_lg_u32 s4, 0
	s_cbranch_scc1 .Lmla_nopf
	s_or_b32 s10, s91, 1
	s_cmp_gt_i32 s10, s34
	s_cbranch_scc1 .Lmla_nopf
	s_or_b32 s10, s88, 1
	s_mulk_i32 s10, 0x5800
	v_add_u32_e32 v173, s10, v246
	s_waitcnt lgkmcnt(3)
	ds_read_b128 v[198:201], v173
	ds_read_b128 v[210:213], v173 offset:1024
	ds_read_b128 v[222:225], v173 offset:2048
	ds_read_b128 v[234:237], v173 offset:3072
	ds_read_b128 v[202:205], v173 offset:4096
	ds_read_b128 v[214:217], v173 offset:5120
	ds_read_b128 v[226:229], v173 offset:6144
	ds_read_b128 v[238:241], v173 offset:7168
	ds_read_b128 v[206:209], v173 offset:8192
	ds_read_b128 v[218:221], v173 offset:9216
	ds_read_b128 v[230:233], v173 offset:10240
	ds_read_b128 v[242:245], v173 offset:11264
.Lmla_nopf:
	s_cmp_gt_i32 s1, s30
	s_cbranch_scc0 .Lmla_nomask
	v_or_b32_e32 v172, s0, v0
	v_sub_u32_e32 v130, v151, v172
	v_sub_u32_e32 v131, v155, v172
	v_cmp_gt_i32_e64 s[38:39], 0, v130
	v_cmp_gt_i32_e64 s[40:41], 1, v130
	v_cmp_gt_i32_e64 s[42:43], 2, v130
	v_cmp_gt_i32_e64 s[44:45], 3, v130
	v_cmp_gt_i32_e64 s[46:47], 16, v130
	v_cmp_gt_i32_e64 s[48:49], 17, v130
	v_cmp_gt_i32_e64 s[50:51], 18, v130
	v_cmp_gt_i32_e64 s[52:53], 19, v130
	v_cndmask_b32_e64 v84, v84, v181, s[38:39]
	v_cndmask_b32_e64 v85, v85, v181, s[40:41]
	v_cndmask_b32_e64 v86, v86, v181, s[42:43]
	v_cndmask_b32_e64 v87, v87, v181, s[44:45]
	v_cndmask_b32_e64 v88, v88, v181, s[46:47]
	v_cndmask_b32_e64 v89, v89, v181, s[48:49]
	v_cndmask_b32_e64 v90, v90, v181, s[50:51]
	v_cndmask_b32_e64 v91, v91, v181, s[52:53]
	v_cmp_gt_i32_e64 s[38:39], 32, v130
	v_cmp_gt_i32_e64 s[40:41], 33, v130
	v_cmp_gt_i32_e64 s[42:43], 34, v130
	v_cmp_gt_i32_e64 s[44:45], 35, v130
	v_cmp_gt_i32_e64 s[46:47], 48, v130
	v_cmp_gt_i32_e64 s[48:49], 49, v130
	v_cmp_gt_i32_e64 s[50:51], 50, v130
	v_cmp_gt_i32_e64 s[52:53], 51, v130
	v_cndmask_b32_e64 v92, v92, v181, s[38:39]
	v_cndmask_b32_e64 v93, v93, v181, s[40:41]
	v_cndmask_b32_e64 v94, v94, v181, s[42:43]
	v_cndmask_b32_e64 v95, v95, v181, s[44:45]
	v_cndmask_b32_e64 v96, v96, v181, s[46:47]
	v_cndmask_b32_e64 v97, v97, v181, s[48:49]
	v_cndmask_b32_e64 v98, v98, v181, s[50:51]
	v_cndmask_b32_e64 v99, v99, v181, s[52:53]
	v_cmp_gt_i32_e64 s[38:39], 0, v131
	v_cmp_gt_i32_e64 s[40:41], 1, v131
	v_cmp_gt_i32_e64 s[42:43], 2, v131
	v_cmp_gt_i32_e64 s[44:45], 3, v131
	v_cmp_gt_i32_e64 s[46:47], 16, v131
	v_cmp_gt_i32_e64 s[48:49], 17, v131
	v_cmp_gt_i32_e64 s[50:51], 18, v131
	v_cmp_gt_i32_e64 s[52:53], 19, v131
	v_cndmask_b32_e64 v100, v100, v181, s[38:39]
	v_cndmask_b32_e64 v101, v101, v181, s[40:41]
	v_cndmask_b32_e64 v102, v102, v181, s[42:43]
	v_cndmask_b32_e64 v103, v103, v181, s[44:45]
	v_cndmask_b32_e64 v104, v104, v181, s[46:47]
	v_cndmask_b32_e64 v105, v105, v181, s[48:49]
	v_cndmask_b32_e64 v106, v106, v181, s[50:51]
	v_cndmask_b32_e64 v107, v107, v181, s[52:53]
	v_cmp_gt_i32_e64 s[38:39], 32, v131
	v_cmp_gt_i32_e64 s[40:41], 33, v131
	v_cmp_gt_i32_e64 s[42:43], 34, v131
	v_cmp_gt_i32_e64 s[44:45], 35, v131
	v_cmp_gt_i32_e64 s[46:47], 48, v131
	v_cmp_gt_i32_e64 s[48:49], 49, v131
	v_cmp_gt_i32_e64 s[50:51], 50, v131
	v_cmp_gt_i32_e64 s[52:53], 51, v131
	v_cndmask_b32_e64 v108, v108, v181, s[38:39]
	v_cndmask_b32_e64 v109, v109, v181, s[40:41]
	v_cndmask_b32_e64 v110, v110, v181, s[42:43]
	v_cndmask_b32_e64 v111, v111, v181, s[44:45]
	v_cndmask_b32_e64 v112, v112, v181, s[46:47]
	v_cndmask_b32_e64 v113, v113, v181, s[48:49]
	v_cndmask_b32_e64 v114, v114, v181, s[50:51]
	v_cndmask_b32_e64 v115, v115, v181, s[52:53]

; #define LAS __attribute__((address_space(3)))
; __device__ __forceinline__ unsigned pkhw(float lo, float hi) { f32x2q v = {lo, hi}; bf16x2q b = __builtin_convertvector(v, bf16x2q); return __builtin_bit_cast(unsigned, b); }
; __device__ __forceinline__ void mla_unit(const Ctx& C, const Params& p, int unit) {
;     ...
;                 const float mn = fmaxf(m[g], mx * c2), alpha = __builtin_amdgcn_exp2f(m[g] - mn); m[g] = mn;
;                 f32x2 ps2 = (f32x2){0.f, 0.f};
;                 const f32x2 c2v = (f32x2){c2, c2}, mnv = (f32x2){mn, mn};
; #pragma unroll
;                 for (int blk = 0; blk < 4; ++blk)
; #pragma unroll
;                     for (int jp = 0; jp < 2; ++jp) { f32x2 x = (f32x2){s[g][blk][2 * jp], s[g][blk][2 * jp + 1]}; x = x * c2v - mnv;
;                         f32x2 pv; pv.x = __builtin_amdgcn_exp2f(x.x); pv.y = __builtin_amdgcn_exp2f(x.y); ps2 = ps2 + pv; s[g][blk][2 * jp] = pv.x; s[g][blk][2 * jp + 1] = pv.y; }
;                 const float ps = ps2.x + ps2.y;
;                 lsum[g] = lsum[g] * alpha + ps;
;                 if (__builtin_amdgcn_ballot_w64(alpha != 1.0f) != 0ull) {
; #pragma unroll
;                     for (int d = 0; d < 4; ++d) o[g][d] = o[g][d] * alpha;
;                 }
; #pragma unroll
;                 for (int hf = 0; hf < 2; ++hf) { v4u pw; pw.x = pkhw(s[g][2 * hf][0], s[g][2 * hf][1]); pw.y = pkhw(s[g][2 * hf][2], s[g][2 * hf][3]); pw.z = pkhw(s[g][2 * hf + 1][0], s[g][2 * hf + 1][1]); pw.w = pkhw(s[g][2 * hf + 1][2], s[g][2 * hf + 1][3]);
;                     pf[g][hf] = __builtin_bit_cast(bf16x8, pw); }
;             }
; #pragma unroll
;             for (int hf = 0; hf < 2; ++hf)
; #pragma unroll
;                 for (int d = 0; d < 4; ++d) {
;                     const bf16x8 vf = *(const LAS bf16x8*)(Vb + (d * 16 + fr) * AV_ROW + (hf * 32 + fq * 8) * 2);
; #pragma unroll
;                     for (int g = 0; g < 2; ++g) o[g][d] = __builtin_amdgcn_mfma_f32_16x16x32_bf16(vf, pf[g][hf], o[g][d], 0, 0, 0);
;                 }
.Lmla_norescale:
	v_exp_f32_e32 v84, v84
	v_exp_f32_e32 v85, v85
	v_exp_f32_e32 v86, v86
	v_exp_f32_e32 v87, v87
	v_exp_f32_e32 v100, v100
	v_exp_f32_e32 v101, v101
	v_exp_f32_e32 v102, v102
	v_exp_f32_e32 v103, v103
	v_exp_f32_e32 v88, v88
	v_exp_f32_e32 v89, v89
	v_exp_f32_e32 v90, v90
	v_exp_f32_e32 v91, v91
	v_exp_f32_e32 v104, v104
	v_exp_f32_e32 v105, v105
	v_exp_f32_e32 v106, v106
	v_exp_f32_e32 v107, v107
	v_pk_add_f32 v[130:131], v[84:85], v[86:87]
	v_pk_add_f32 v[132:133], v[100:101], v[102:103]
	v_pk_add_f32 v[130:131], v[130:131], v[88:89]
	v_pk_add_f32 v[132:133], v[132:133], v[104:105]
	v_pk_add_f32 v[130:131], v[130:131], v[90:91]
	v_pk_add_f32 v[132:133], v[132:133], v[106:107]
	v_cvt_pk_bf16_f32 v84, v84, v85
	v_cvt_pk_bf16_f32 v85, v86, v87
	v_cvt_pk_bf16_f32 v86, v88, v89
	v_cvt_pk_bf16_f32 v87, v90, v91
	v_cvt_pk_bf16_f32 v100, v100, v101
	v_cvt_pk_bf16_f32 v101, v102, v103
	v_cvt_pk_bf16_f32 v102, v104, v105
	v_cvt_pk_bf16_f32 v103, v106, v107
	s_waitcnt lgkmcnt(4)
	v_mfma_f32_16x16x32_bf16 v[72:75], v[134:137], v[84:87], v[72:75]
	v_pk_fma_f32 v[92:93], v[92:93], s[60:61], v[2:3] op_sel_hi:[1,0,0] neg_lo:[0,0,1] neg_hi:[0,0,1]
	v_pk_fma_f32 v[94:95], v[94:95], s[60:61], v[2:3] op_sel_hi:[1,0,0] neg_lo:[0,0,1] neg_hi:[0,0,1]
	v_pk_fma_f32 v[108:109], v[108:109], s[60:61], v[150:151] op_sel_hi:[1,0,0] neg_lo:[0,0,1] neg_hi:[0,0,1]
	v_pk_fma_f32 v[110:111], v[110:111], s[60:61], v[150:151] op_sel_hi:[1,0,0] neg_lo:[0,0,1] neg_hi:[0,0,1]
	v_pk_fma_f32 v[96:97], v[96:97], s[60:61], v[2:3] op_sel_hi:[1,0,0] neg_lo:[0,0,1] neg_hi:[0,0,1]
	v_pk_fma_f32 v[98:99], v[98:99], s[60:61], v[2:3] op_sel_hi:[1,0,0] neg_lo:[0,0,1] neg_hi:[0,0,1]
	v_mfma_f32_16x16x32_bf16 v[52:55], v[134:137], v[100:103], v[52:55]
	v_pk_fma_f32 v[112:113], v[112:113], s[60:61], v[150:151] op_sel_hi:[1,0,0] neg_lo:[0,0,1] neg_hi:[0,0,1]
	v_pk_fma_f32 v[114:115], v[114:115], s[60:61], v[150:151] op_sel_hi:[1,0,0] neg_lo:[0,0,1] neg_hi:[0,0,1]
	v_exp_f32_e32 v92, v92
	v_exp_f32_e32 v93, v93
	v_exp_f32_e32 v94, v94
	v_exp_f32_e32 v95, v95
	v_mfma_f32_16x16x32_bf16 v[64:67], v[138:141], v[84:87], v[64:67]
	v_exp_f32_e32 v108, v108
	v_exp_f32_e32 v109, v109
	v_exp_f32_e32 v110, v110
	v_exp_f32_e32 v111, v111
	v_exp_f32_e32 v96, v96
	v_exp_f32_e32 v97, v97
	v_mfma_f32_16x16x32_bf16 v[48:51], v[138:141], v[100:103], v[48:51]
	v_exp_f32_e32 v98, v98
	v_exp_f32_e32 v99, v99
	v_exp_f32_e32 v112, v112
	v_exp_f32_e32 v113, v113
	v_exp_f32_e32 v114, v114
	v_exp_f32_e32 v115, v115
	v_mfma_f32_16x16x32_bf16 v[68:71], v[142:145], v[84:87], v[68:71]
	v_pk_add_f32 v[130:131], v[130:131], v[92:93]
	v_pk_add_f32 v[132:133], v[132:133], v[108:109]
	v_pk_add_f32 v[130:131], v[130:131], v[94:95]
	v_pk_add_f32 v[132:133], v[132:133], v[110:111]
	v_pk_add_f32 v[130:131], v[130:131], v[96:97]
	v_pk_add_f32 v[132:133], v[132:133], v[112:113]
	v_mfma_f32_16x16x32_bf16 v[56:59], v[142:145], v[100:103], v[56:59]
	v_pk_add_f32 v[130:131], v[130:131], v[98:99]
	v_pk_add_f32 v[132:133], v[132:133], v[114:115]
	v_add_f32_e32 v130, v130, v131
	v_add_f32_e32 v132, v132, v133
	v_fma_f32 v190, v190, v152, v130
	v_fma_f32 v191, v191, v154, v132
	v_mfma_f32_16x16x32_bf16 v[80:83], v[146:149], v[84:87], v[80:83]
	v_cvt_pk_bf16_f32 v92, v92, v93
	v_cvt_pk_bf16_f32 v93, v94, v95
	v_cvt_pk_bf16_f32 v94, v96, v97
	v_cvt_pk_bf16_f32 v95, v98, v99
	v_cvt_pk_bf16_f32 v108, v108, v109
	v_cvt_pk_bf16_f32 v109, v110, v111
	v_mfma_f32_16x16x32_bf16 v[76:79], v[146:149], v[100:103], v[76:79]
	v_cvt_pk_bf16_f32 v110, v112, v113
	v_cvt_pk_bf16_f32 v111, v114, v115
	s_waitcnt lgkmcnt(0)
	v_mfma_f32_16x16x32_bf16 v[72:75], v[160:163], v[92:95], v[72:75]
	v_mfma_f32_16x16x32_bf16 v[52:55], v[160:163], v[108:111], v[52:55]
	v_mfma_f32_16x16x32_bf16 v[64:67], v[164:167], v[92:95], v[64:67]
	v_mfma_f32_16x16x32_bf16 v[48:51], v[164:167], v[108:111], v[48:51]
	v_mfma_f32_16x16x32_bf16 v[68:71], v[168:171], v[92:95], v[68:71]
	v_mfma_f32_16x16x32_bf16 v[56:59], v[168:171], v[108:111], v[56:59]
	v_mfma_f32_16x16x32_bf16 v[80:83], v[156:159], v[92:95], v[80:83]
	v_mfma_f32_16x16x32_bf16 v[76:79], v[156:159], v[108:111], v[76:79]

; __device__ __forceinline__ void xcd_barrier(const XcdBarrier& b) {
;     asm volatile("s_waitcnt vmcnt(0)" ::: "memory");
;     __syncthreads();
;     if (threadIdx.x == 0) {
;         unsigned* bar = b.bar;
;         __builtin_amdgcn_s_waitcnt(0);
;         unsigned nloc = b.st[0], nx = b.st[1];
;         if (nloc == 0u) { xcd_barrier_complete(bar, b.x, nloc, nx); b.st[0] = nloc; b.st[1] = nx; }
.LBB0_535:
	v_mov_b64_e32 v[134:135], 0x180
	v_mov_b64_e32 v[136:137], 0x17f
	v_mov_b64_e32 v[138:139], 0x100
	v_mov_b64_e32 v[140:141], 0xff
	v_mov_b64_e32 v[142:143], 0x200
	v_mov_b64_e32 v[144:145], 0x1ff
	v_mov_b64_e32 v[146:147], 0x800
	v_mov_b64_e32 v[148:149], 0x7ff
	s_waitcnt vmcnt(0)
	s_barrier
	s_mov_b64 s[0:1], exec
	v_readlane_b32 s8, v251, 9
	v_readlane_b32 s9, v251, 10
	s_and_b64 s[8:9], s[0:1], s[8:9]
	s_mov_b64 exec, s[8:9]
	s_cbranch_execz .LBB0_587
	v_readlane_b32 s4, v254, 45
	s_waitcnt vmcnt(0) expcnt(0) lgkmcnt(0)
	s_nop 0
	v_mov_b32_e32 v0, s4
	ds_read_b32 v3, v0
	v_readlane_b32 s4, v254, 46
	s_waitcnt lgkmcnt(0)
	v_cmp_ne_u32_e32 vcc, 0, v3
	v_mov_b32_e32 v0, s4
	ds_read_b32 v2, v0
	s_cbranch_vccnz .LBB0_551
	s_mov_b32 s4, 1
	s_branch .LBB0_539
